# v36 + band attention output stores merged 4x dwordx2 -> 2x dwordx4 via permlane32/16 exchange
# speedup vs baseline: 1.0061x; 1.0047x over previous
; __device__ __forceinline__ unsigned cvt_pk_bf16(float lo, float hi) { const f32x2 v = {lo, hi}; const bf16x2_t b = __builtin_convertvector(v, bf16x2_t); return __builtin_bit_cast(unsigned, b); }
; __device__ __forceinline__ float fast_rcp(float x) { return __builtin_amdgcn_rcpf(x); }
; __device__ __forceinline__ float xsum16(float v) { const auto r = __builtin_amdgcn_permlane16_swap(__float_as_uint(v), __float_as_uint(v), false, false); return __uint_as_float(r[0]) + __uint_as_float(r[1]); }
; __device__ __forceinline__ float xsum32(float v) { const auto r = __builtin_amdgcn_permlane32_swap(__float_as_uint(v), __float_as_uint(v), false, false); return __uint_as_float(r[0]) + __uint_as_float(r[1]); }
; __device__ __forceinline__ void attn_store(const f32x4 (&o)[4], float inv, bf16_t* op, int g4) {
; #pragma unroll
;     for (int db = 0; db < 4; ++db) { u32x2 w; w.x = cvt_pk_bf16(o[db][0] * inv, o[db][1] * inv); w.y = cvt_pk_bf16(o[db][2] * inv, o[db][3] * inv); *(u32x2*)(op + 16 * db + 4 * g4) = w; }
; }
; template <int NQ>
; __device__ __forceinline__ void band_unit(int u, const bf16_t* P, bf16_t* OB, bf16_t* ACX, float* LSE, const float* sink, LAS unsigned char* vl, int lane_in) {
;     ...
;     for (int g = 0; g < NQ; ++g) {
;         const size_t tq = rowbase + (size_t)d * (q0 + 16 * g + qi);
;         float lt = l[g]; lt = xsum32(xsum16(lt));
;         bf16_t* op = (cfg == 0) ? OB + tq * NO_ + h * 64 : (cfg == 3) ? OB + tq * NO_ + 512 + h * 64 : ACX + (size_t)(cfg - 1) * T_ * 512 + tq * 512 + h * 64;
;         attn_store(o[g], fast_rcp(lt), op, g4);
;         if (cfg < 3 && g4 == 0) LSE[(size_t)cfg * T_ * 8 + tq * 8 + h] = m[g] + __log2f(lt);
;     }
.LBB0_1275:
	v_add_f32_e32 v0, v0, v54
	v_rcp_f32_e32 v54, v0
	v_lshl_add_u64 v[52:53], v[50:51], 1, v[52:53]
	v_pk_mul_f32 v[46:47], v[46:47], v[54:55] op_sel_hi:[1,0]
	v_pk_mul_f32 v[48:49], v[48:49], v[54:55] op_sel_hi:[1,0]
	v_pk_mul_f32 v[42:43], v[42:43], v[54:55] op_sel_hi:[1,0]
	v_pk_mul_f32 v[44:45], v[44:45], v[54:55] op_sel_hi:[1,0]
	v_pk_mul_f32 v[38:39], v[38:39], v[54:55] op_sel_hi:[1,0]
	v_pk_mul_f32 v[40:41], v[40:41], v[54:55] op_sel_hi:[1,0]
	v_pk_mul_f32 v[34:35], v[34:35], v[54:55] op_sel_hi:[1,0]
	v_pk_mul_f32 v[36:37], v[36:37], v[54:55] op_sel_hi:[1,0]
	v_cvt_pk_bf16_f32 v46, v46, v47
	v_cvt_pk_bf16_f32 v47, v48, v49
	v_cvt_pk_bf16_f32 v42, v42, v43
	v_cvt_pk_bf16_f32 v43, v44, v45
	v_cvt_pk_bf16_f32 v38, v38, v39
	v_cvt_pk_bf16_f32 v39, v40, v41
	v_cvt_pk_bf16_f32 v34, v34, v35
	v_cvt_pk_bf16_f32 v35, v36, v37
	v_mov_b32_e32 v48, v42
	v_mov_b32_e32 v49, v43
	v_mov_b32_e32 v40, v34
	v_mov_b32_e32 v41, v35
	v_bfe_u32 v44, v227, 4, 2
	v_lshlrev_b32_e32 v44, 3, v44
	v_mov_b32_e32 v45, 0
	v_lshl_add_u64 v[44:45], v[52:53], 0, v[44:45]
	v_permlane32_swap_b32_e32 v46, v48
	v_permlane32_swap_b32_e32 v47, v49
	v_permlane32_swap_b32_e32 v38, v40
	v_permlane32_swap_b32_e32 v39, v41
	v_permlane16_swap_b32_e32 v46, v48
	v_permlane16_swap_b32_e32 v47, v49
	v_permlane16_swap_b32_e32 v38, v40
	v_permlane16_swap_b32_e32 v39, v41
	global_store_dwordx4 v[44:45], v[46:49], off
	global_store_dwordx4 v[44:45], v[38:41], off offset:64
	s_and_saveexec_b64 s[12:13], s[6:7]
	v_readlane_b32 s24, v250, 5
	v_readlane_b32 s25, v250, 6
	v_readlane_b32 s30, v250, 11
	v_readlane_b32 s31, v250, 12
	v_readlane_b32 s26, v250, 7
	v_readlane_b32 s27, v250, 8
	v_readlane_b32 s28, v250, 9
	v_readlane_b32 s29, v250, 10
	s_cbranch_execz .LBB0_1277
	v_log_f32_e32 v0, v0
	v_lshlrev_b64 v[34:35], 5, v[182:183]
	v_lshl_add_u64 v[34:35], s[8:9], 0, v[34:35]
	v_add_f32_e32 v0, v220, v0
	global_store_dword v[34:35], v0, off

; __device__ __forceinline__ unsigned cvt_pk_bf16(float lo, float hi) { const f32x2 v = {lo, hi}; const bf16x2_t b = __builtin_convertvector(v, bf16x2_t); return __builtin_bit_cast(unsigned, b); }
; __device__ __forceinline__ float fast_rcp(float x) { return __builtin_amdgcn_rcpf(x); }
; __device__ __forceinline__ float xsum16(float v) { const auto r = __builtin_amdgcn_permlane16_swap(__float_as_uint(v), __float_as_uint(v), false, false); return __uint_as_float(r[0]) + __uint_as_float(r[1]); }
; __device__ __forceinline__ float xsum32(float v) { const auto r = __builtin_amdgcn_permlane32_swap(__float_as_uint(v), __float_as_uint(v), false, false); return __uint_as_float(r[0]) + __uint_as_float(r[1]); }
; __device__ __forceinline__ void attn_store(const f32x4 (&o)[4], float inv, bf16_t* op, int g4) {
; #pragma unroll
;     for (int db = 0; db < 4; ++db) { u32x2 w; w.x = cvt_pk_bf16(o[db][0] * inv, o[db][1] * inv); w.y = cvt_pk_bf16(o[db][2] * inv, o[db][3] * inv); *(u32x2*)(op + 16 * db + 4 * g4) = w; }
; }
; template <int NQ>
; __device__ __forceinline__ void band_unit(int u, const bf16_t* P, bf16_t* OB, bf16_t* ACX, float* LSE, const float* sink, LAS unsigned char* vl, int lane_in) {
;     ...
;     for (int g = 0; g < NQ; ++g) {
;         const size_t tq = rowbase + (size_t)d * (q0 + 16 * g + qi);
;         float lt = l[g]; lt = xsum32(xsum16(lt));
;         bf16_t* op = (cfg == 0) ? OB + tq * NO_ + h * 64 : (cfg == 3) ? OB + tq * NO_ + 512 + h * 64 : ACX + (size_t)(cfg - 1) * T_ * 512 + tq * 512 + h * 64;
;         attn_store(o[g], fast_rcp(lt), op, g4);
;         if (cfg < 3 && g4 == 0) LSE[(size_t)cfg * T_ * 8 + tq * 8 + h] = m[g] + __log2f(lt);
;     }
.LBB0_1285:
	v_add_f32_e32 v0, v0, v36
	v_rcp_f32_e32 v36, v0
	v_lshl_add_u64 v[34:35], v[50:51], 1, v[34:35]
	v_pk_mul_f32 v[30:31], v[30:31], v[36:37] op_sel_hi:[1,0]
	v_pk_mul_f32 v[32:33], v[32:33], v[36:37] op_sel_hi:[1,0]
	v_pk_mul_f32 v[26:27], v[26:27], v[36:37] op_sel_hi:[1,0]
	v_pk_mul_f32 v[28:29], v[28:29], v[36:37] op_sel_hi:[1,0]
	v_pk_mul_f32 v[22:23], v[22:23], v[36:37] op_sel_hi:[1,0]
	v_pk_mul_f32 v[24:25], v[24:25], v[36:37] op_sel_hi:[1,0]
	v_pk_mul_f32 v[18:19], v[18:19], v[36:37] op_sel_hi:[1,0]
	v_pk_mul_f32 v[20:21], v[20:21], v[36:37] op_sel_hi:[1,0]
	v_cvt_pk_bf16_f32 v30, v30, v31
	v_cvt_pk_bf16_f32 v31, v32, v33
	v_cvt_pk_bf16_f32 v26, v26, v27
	v_cvt_pk_bf16_f32 v27, v28, v29
	v_cvt_pk_bf16_f32 v22, v22, v23
	v_cvt_pk_bf16_f32 v23, v24, v25
	v_cvt_pk_bf16_f32 v18, v18, v19
	v_cvt_pk_bf16_f32 v19, v20, v21
	v_mov_b32_e32 v32, v26
	v_mov_b32_e32 v33, v27
	v_mov_b32_e32 v24, v18
	v_mov_b32_e32 v25, v19
	v_bfe_u32 v28, v227, 4, 2
	v_lshlrev_b32_e32 v28, 3, v28
	v_mov_b32_e32 v29, 0
	v_lshl_add_u64 v[28:29], v[34:35], 0, v[28:29]
	v_permlane32_swap_b32_e32 v30, v32
	v_permlane32_swap_b32_e32 v31, v33
	v_permlane32_swap_b32_e32 v22, v24
	v_permlane32_swap_b32_e32 v23, v25
	v_permlane16_swap_b32_e32 v30, v32
	v_permlane16_swap_b32_e32 v31, v33
	v_permlane16_swap_b32_e32 v22, v24
	v_permlane16_swap_b32_e32 v23, v25
	global_store_dwordx4 v[28:29], v[30:33], off
	global_store_dwordx4 v[28:29], v[22:25], off offset:64
	s_and_saveexec_b64 s[12:13], s[6:7]
	s_cbranch_execz .LBB0_1287
	v_log_f32_e32 v0, v0
	v_lshlrev_b64 v[18:19], 5, v[180:181]
	v_lshl_add_u64 v[18:19], s[8:9], 0, v[18:19]
	v_add_f32_e32 v0, v219, v0
	global_store_dword v[18:19], v0, off

; __device__ __forceinline__ unsigned cvt_pk_bf16(float lo, float hi) { const f32x2 v = {lo, hi}; const bf16x2_t b = __builtin_convertvector(v, bf16x2_t); return __builtin_bit_cast(unsigned, b); }
; __device__ __forceinline__ float fast_rcp(float x) { return __builtin_amdgcn_rcpf(x); }
; __device__ __forceinline__ float xsum16(float v) { const auto r = __builtin_amdgcn_permlane16_swap(__float_as_uint(v), __float_as_uint(v), false, false); return __uint_as_float(r[0]) + __uint_as_float(r[1]); }
; __device__ __forceinline__ float xsum32(float v) { const auto r = __builtin_amdgcn_permlane32_swap(__float_as_uint(v), __float_as_uint(v), false, false); return __uint_as_float(r[0]) + __uint_as_float(r[1]); }
; __device__ __forceinline__ void attn_store(const f32x4 (&o)[4], float inv, bf16_t* op, int g4) {
; #pragma unroll
;     for (int db = 0; db < 4; ++db) { u32x2 w; w.x = cvt_pk_bf16(o[db][0] * inv, o[db][1] * inv); w.y = cvt_pk_bf16(o[db][2] * inv, o[db][3] * inv); *(u32x2*)(op + 16 * db + 4 * g4) = w; }
; }
; template <int NQ>
; __device__ __forceinline__ void band_unit(int u, const bf16_t* P, bf16_t* OB, bf16_t* ACX, float* LSE, const float* sink, LAS unsigned char* vl, int lane_in) {
;     ...
;     for (int g = 0; g < NQ; ++g) {
;         const size_t tq = rowbase + (size_t)d * (q0 + 16 * g + qi);
;         float lt = l[g]; lt = xsum32(xsum16(lt));
;         bf16_t* op = (cfg == 0) ? OB + tq * NO_ + h * 64 : (cfg == 3) ? OB + tq * NO_ + 512 + h * 64 : ACX + (size_t)(cfg - 1) * T_ * 512 + tq * 512 + h * 64;
;         attn_store(o[g], fast_rcp(lt), op, g4);
;         if (cfg < 3 && g4 == 0) LSE[(size_t)cfg * T_ * 8 + tq * 8 + h] = m[g] + __log2f(lt);
;     }
.LBB0_1295:
	v_add_f32_e32 v0, v0, v20
	v_rcp_f32_e32 v20, v0
	v_lshl_add_u64 v[18:19], v[50:51], 1, v[18:19]
	v_pk_mul_f32 v[14:15], v[14:15], v[20:21] op_sel_hi:[1,0]
	v_pk_mul_f32 v[16:17], v[16:17], v[20:21] op_sel_hi:[1,0]
	v_pk_mul_f32 v[10:11], v[10:11], v[20:21] op_sel_hi:[1,0]
	v_pk_mul_f32 v[12:13], v[12:13], v[20:21] op_sel_hi:[1,0]
	v_pk_mul_f32 v[6:7], v[6:7], v[20:21] op_sel_hi:[1,0]
	v_pk_mul_f32 v[8:9], v[8:9], v[20:21] op_sel_hi:[1,0]
	v_pk_mul_f32 v[2:3], v[2:3], v[20:21] op_sel_hi:[1,0]
	v_pk_mul_f32 v[4:5], v[4:5], v[20:21] op_sel_hi:[1,0]
	v_cvt_pk_bf16_f32 v14, v14, v15
	v_cvt_pk_bf16_f32 v15, v16, v17
	v_cvt_pk_bf16_f32 v10, v10, v11
	v_cvt_pk_bf16_f32 v11, v12, v13
	v_cvt_pk_bf16_f32 v6, v6, v7
	v_cvt_pk_bf16_f32 v7, v8, v9
	v_cvt_pk_bf16_f32 v2, v2, v3
	v_cvt_pk_bf16_f32 v3, v4, v5
	v_mov_b32_e32 v16, v10
	v_mov_b32_e32 v17, v11
	v_mov_b32_e32 v8, v2
	v_mov_b32_e32 v9, v3
	v_bfe_u32 v12, v227, 4, 2
	v_lshlrev_b32_e32 v12, 3, v12
	v_mov_b32_e32 v13, 0
	v_lshl_add_u64 v[12:13], v[18:19], 0, v[12:13]
	v_permlane32_swap_b32_e32 v14, v16
	v_permlane32_swap_b32_e32 v15, v17
	v_permlane32_swap_b32_e32 v6, v8
	v_permlane32_swap_b32_e32 v7, v9
	v_permlane16_swap_b32_e32 v14, v16
	v_permlane16_swap_b32_e32 v15, v17
	v_permlane16_swap_b32_e32 v6, v8
	v_permlane16_swap_b32_e32 v7, v9
	global_store_dwordx4 v[12:13], v[14:17], off
	global_store_dwordx4 v[12:13], v[6:9], off offset:64
	s_and_saveexec_b64 s[4:5], s[6:7]
	s_cbranch_execz .LBB0_1199
	v_log_f32_e32 v0, v0
	v_lshlrev_b64 v[2:3], 5, v[178:179]
	v_lshl_add_u64 v[2:3], s[8:9], 0, v[2:3]
	v_add_f32_e32 v0, v218, v0
	global_store_dword v[2:3], v0, off
	s_branch .LBB0_1199
